# mLSTM chunk loop: removed the now-redundant workgroup barrier between the QC^T stage and the numerator stage; RWKV RA items: 40 serial per-element parameter dword loads replaced by 10 quad loads issue
# speedup vs baseline: 1.1486x; 1.0045x over previous
; __device__ __forceinline__ float sigmoidf_(float x) { return __builtin_amdgcn_rcpf(1.0f + __expf(-x)); }
; __device__ __forceinline__ float softplusf_(float x) { return fmaxf(x, 0.f) + __logf(1.0f + __expf(-fabsf(x))); }
; __device__ __forceinline__ void phase_rwkv_ra(const Ctx& c, int p, int l) {
;     ...
;             const float* pw0 = inp(c, I_W0) + (size_t)l * D + col; const float* pa0 = inp(c, I_A0) + (size_t)l * D + col; const float* pkk = inp(c, I_KK) + (size_t)l * D + col;
;             const float* pka = inp(c, I_KA) + (size_t)l * D + col; const float* prk = inp(c, I_RK) + (size_t)l * D + col;
;             float ssq = 0.f, bsum = 0.f;
; #pragma unroll
;             for (int e = 0; e < 8; ++e) {
;                 if (valid) {
;                     const float wlog = -softplusf_(-(pw0[e] + wpf[e])) - 0.5f; lw[e] = -__expf(wlog);
;                     const float a = sigmoidf_(pa0[e] + apf[e]); const float kk = kf[e] * pkk[e]; ssq += kk * kk;
;                     kp[e] = kf[e] * (1.0f + (a - 1.0f) * pka[e]); bsum += rf[e] * kp[e] * prk[e]; av[e] = kk; bv[e] = a;
;                 } else { lw[e] = 0.f; rf[e] = 0.f; kp[e] = 0.f; av[e] = 0.f; bv[e] = 0.f; }
;             }
;             ssq += __shfl_xor(ssq, 1); ssq += __shfl_xor(ssq, 2); ssq += __shfl_xor(ssq, 4);
;             bsum += __shfl_xor(bsum, 1); bsum += __shfl_xor(bsum, 2); bsum += __shfl_xor(bsum, 4);
;             const float inv = __builtin_amdgcn_rsqf(fmaxf(ssq, 1e-24f));
; #pragma unroll
;             for (int e = 0; e < 8; ++e) { const float kk = av[e] * inv; av[e] = -kk; bv[e] = kk * bv[e]; }
;             if (jp == 0) { bon[t] = bsum; if (!sample) bonus_g[(size_t)(rbase + t) * 16 + h] = bsum; }
;         }
.LBB0_1215:
	v_mov_b32_e32 v8, s45
	ds_read2_b32 v[8:9], v8 offset1:1
	v_readlane_b32 s10, v254, 34
	v_readlane_b32 s11, v254, 35
	s_lshl_b64 s[12:13], s[10:11], 2
	s_waitcnt lgkmcnt(0)
	v_readfirstlane_b32 s0, v8
	v_mov_b32_e32 v8, s46
	v_readfirstlane_b32 s7, v9
	ds_read2_b32 v[8:9], v8 offset1:1
	s_add_u32 s6, s0, s12
	s_addc_u32 s7, s7, s13
	s_waitcnt lgkmcnt(0)
	v_readfirstlane_b32 s0, v8
	v_mov_b32_e32 v8, s47
	v_readfirstlane_b32 s11, v9
	ds_read2_b32 v[8:9], v8 offset1:1
	s_add_u32 s10, s0, s12
	s_addc_u32 s11, s11, s13
	s_waitcnt lgkmcnt(0)
	v_readfirstlane_b32 s0, v8
	v_mov_b32_e32 v8, s48
	v_readfirstlane_b32 s31, v9
	ds_read2_b32 v[8:9], v8 offset1:1
	s_add_u32 s30, s0, s12
	s_addc_u32 s31, s31, s13
	s_waitcnt lgkmcnt(0)
	v_readfirstlane_b32 s0, v8
	v_mov_b32_e32 v8, s49
	v_readfirstlane_b32 s35, v9
	ds_read2_b32 v[8:9], v8 offset1:1
	s_add_u32 s34, s0, s12
	s_addc_u32 s35, s35, s13
	s_waitcnt lgkmcnt(0)
	v_readfirstlane_b32 s0, v8
	v_readfirstlane_b32 s37, v9
	s_add_u32 s36, s0, s12
	s_addc_u32 s37, s37, s13
	s_and_saveexec_b64 s[12:13], s[4:5]
	s_xor_b64 s[12:13], exec, s[12:13]
	v_mov_b32_e32 v16, s91
	s_or_saveexec_b64 s[12:13], s[12:13]
	v_lshlrev_b32_e32 v30, 2, v28
	v_lshl_add_u64 v[76:77], s[6:7], 0, v[30:31]
	v_lshl_add_u64 v[70:71], s[10:11], 0, v[30:31]
	v_lshl_add_u64 v[62:63], s[30:31], 0, v[30:31]
	v_lshl_add_u64 v[72:73], s[34:35], 0, v[30:31]
	v_lshl_add_u64 v[64:65], s[36:37], 0, v[30:31]
	v_mov_b32_e32 v30, v31
	v_mov_b32_e32 v126, 0
	v_mov_b32_e32 v127, 0
	v_mov_b32_e32 v29, 0
	v_mov_b32_e32 v28, 0
	v_mov_b64_e32 v[68:69], v[30:31]
	global_load_dwordx4 v[200:203], v[76:77], off
	global_load_dwordx4 v[204:207], v[76:77], off offset:16
	global_load_dwordx4 v[208:211], v[70:71], off
	global_load_dwordx4 v[212:215], v[70:71], off offset:16
	global_load_dwordx4 v[216:219], v[72:73], off
	global_load_dwordx4 v[220:223], v[72:73], off offset:16
	global_load_dwordx4 v[224:227], v[62:63], off
	global_load_dwordx4 v[228:231], v[62:63], off offset:16
	global_load_dwordx4 v[232:235], v[64:65], off
	global_load_dwordx4 v[236:239], v[64:65], off offset:16
	s_waitcnt vmcnt(0)
	s_xor_b64 exec, exec, s[12:13]
	s_cbranch_execz .LBB0_1219
	v_mov_b32_e32 v10, v200
	v_mov_b32_e32 v12, v208
	v_mov_b32_e32 v13, v216
	v_mov_b32_e32 v9, v224
	v_mov_b32_e32 v8, v232
	s_mov_b32 s0, 0xbfb8aa3b
	v_mov_b32_e32 v11, v0
	v_add_f32_e32 v10, v105, v10
	v_mul_f32_e64 v14, |v10|, s0
	v_add_f32_e32 v12, v113, v12
	v_exp_f32_e32 v14, v14
	v_mul_f32_e32 v12, 0xbfb8aa3b, v12
	v_exp_f32_e32 v15, v12
	v_max_f32_e64 v30, -v10, 0
	v_add_f32_e32 v10, 1.0, v14
	s_mov_b32 s0, 0x800000
	v_cmp_gt_f32_e32 vcc, s0, v10
	v_add_f32_e32 v14, 1.0, v15
	v_rcp_f32_e32 v127, v14
	v_cndmask_b32_e64 v15, 0, 32, vcc
	v_ldexp_f32 v10, v10, v15
	v_log_f32_e32 v14, v10
	v_add_f32_e32 v10, -1.0, v127
	v_fma_f32 v10, v13, v10, 1.0
	s_mov_b32 s0, 0x3f317217
	v_mul_f32_e32 v13, 0x3f317217, v14
	v_fma_f32 v13, v14, s0, -v13
	v_fmac_f32_e32 v13, 0x3377d1cf, v14
	s_mov_b32 s0, 0x7f800000
	v_cndmask_b32_e32 v15, 0, v178, vcc
	v_fmac_f32_e32 v13, 0x3f317217, v14
	v_cmp_lt_f32_e64 vcc, |v14|, s0
	v_mul_f32_e32 v126, v0, v10
	v_mul_f32_e32 v10, v16, v126
	v_cndmask_b32_e32 v13, v14, v13, vcc
	v_sub_f32_e32 v13, v13, v15
	v_add_f32_e32 v13, v30, v13
	v_sub_f32_e32 v13, -0.5, v13
	v_mul_f32_e32 v13, 0x3fb8aa3b, v13
	v_exp_f32_e32 v30, v13
	v_pk_mul_f32 v[28:29], v[8:9], v[10:11]
	v_mov_b32_e32 v12, v31
	v_mov_b32_e32 v13, v29
	v_pk_mul_f32 v[14:15], v[28:29], v[28:29]
	v_pk_fma_f32 v[68:69], v[8:9], v[10:11], v[12:13]
	v_xor_b32_e32 v28, 0x80000000, v30
	v_mov_b32_e32 v69, v15
.LBB0_1219:
	s_or_b64 exec, exec, s[12:13]
	s_and_saveexec_b64 s[6:7], s[4:5]
	s_xor_b64 s[6:7], exec, s[6:7]
	v_mov_b32_e32 v17, s91
	s_or_saveexec_b64 s[6:7], s[6:7]
	v_mov_b32_e32 v30, 0
	v_mov_b32_e32 v131, 0
	v_mov_b32_e32 v32, 0
	v_mov_b32_e32 v33, 0
	s_xor_b64 exec, exec, s[6:7]
	s_cbranch_execz .LBB0_1223
	v_mov_b32_e32 v9, v201
	v_mov_b32_e32 v11, v209
	v_mov_b32_e32 v12, v217
	v_mov_b32_e32 v8, v225
	v_mov_b32_e32 v10, v233
	s_mov_b32 s0, 0xbfb8aa3b
	v_add_f32_e32 v9, v106, v9
	v_add_f32_e32 v11, v114, v11
	v_mul_f32_e64 v13, |v9|, s0
	v_mul_f32_e32 v11, 0xbfb8aa3b, v11
	v_exp_f32_e32 v13, v13
	v_exp_f32_e32 v11, v11
	v_max_f32_e64 v14, -v9, 0
	s_mov_b32 s0, 0x800000
	v_add_f32_e32 v9, 1.0, v13
	v_add_f32_e32 v11, 1.0, v11
	v_cmp_gt_f32_e32 vcc, s0, v9
	v_rcp_f32_e32 v30, v11
	s_mov_b32 s0, 0x3f317217
	v_cndmask_b32_e64 v11, 0, 32, vcc
	v_ldexp_f32 v9, v9, v11
	v_log_f32_e32 v11, v9
	v_add_f32_e32 v9, -1.0, v30
	v_fma_f32 v9, v12, v9, 1.0
	v_pk_mul_f32 v[32:33], v[0:1], v[8:9] op_sel:[1,0]
	v_mul_f32_e32 v8, 0x3f317217, v11
	v_fma_f32 v8, v11, s0, -v8
	v_fmac_f32_e32 v8, 0x3377d1cf, v11
	s_mov_b32 s0, 0x7f800000
	v_cndmask_b32_e32 v13, 0, v178, vcc
	v_fmac_f32_e32 v8, 0x3f317217, v11
	v_cmp_lt_f32_e64 vcc, |v11|, s0
	v_mov_b32_e32 v9, v32
	s_nop 0
	v_cndmask_b32_e32 v8, v11, v8, vcc
	v_sub_f32_e32 v8, v8, v13
	v_add_f32_e32 v8, v14, v8
	v_sub_f32_e32 v8, -0.5, v8
	v_mul_f32_e32 v8, 0x3fb8aa3b, v8
	v_exp_f32_e32 v12, v8
	v_mul_f32_e32 v8, v17, v33
	v_mov_b32_e32 v11, v32
	v_pk_fma_f32 v[68:69], v[10:11], v[8:9], v[68:69]
	v_xor_b32_e32 v131, 0x80000000, v12
; __device__ __forceinline__ float sigmoidf_(float x) { return __builtin_amdgcn_rcpf(1.0f + __expf(-x)); }
; __device__ __forceinline__ float softplusf_(float x) { return fmaxf(x, 0.f) + __logf(1.0f + __expf(-fabsf(x))); }
; __device__ __forceinline__ void phase_rwkv_ra(const Ctx& c, int p, int l) {
;     ...
;             float ssq = 0.f, bsum = 0.f;
; #pragma unroll
;             for (int e = 0; e < 8; ++e) {
;                 if (valid) {
;                     const float wlog = -softplusf_(-(pw0[e] + wpf[e])) - 0.5f; lw[e] = -__expf(wlog);
;                     const float a = sigmoidf_(pa0[e] + apf[e]); const float kk = kf[e] * pkk[e]; ssq += kk * kk;
;                     kp[e] = kf[e] * (1.0f + (a - 1.0f) * pka[e]); bsum += rf[e] * kp[e] * prk[e]; av[e] = kk; bv[e] = a;
;                 } else { lw[e] = 0.f; rf[e] = 0.f; kp[e] = 0.f; av[e] = 0.f; bv[e] = 0.f; }
;             }
.LBB0_1223:
	s_or_b64 exec, exec, s[6:7]
	s_and_saveexec_b64 s[6:7], s[4:5]
	s_xor_b64 s[6:7], exec, s[6:7]
	v_mov_b32_e32 v18, s91
	s_or_saveexec_b64 s[6:7], s[6:7]
	v_mov_b32_e32 v129, 0
	v_mov_b32_e32 v132, 0
	v_mov_b32_e32 v34, 0
	v_mov_b32_e32 v35, 0
	s_xor_b64 exec, exec, s[6:7]
	s_cbranch_execz .LBB0_1227
	v_mov_b32_e32 v9, v202
	v_mov_b32_e32 v11, v210
	v_mov_b32_e32 v12, v218
	v_mov_b32_e32 v8, v226
	v_mov_b32_e32 v10, v234
	s_mov_b32 s0, 0xbfb8aa3b
	v_add_f32_e32 v9, v107, v9
	v_add_f32_e32 v11, v115, v11
	v_mul_f32_e64 v13, |v9|, s0
	v_mul_f32_e32 v11, 0xbfb8aa3b, v11
	v_exp_f32_e32 v13, v13
	v_exp_f32_e32 v11, v11
	v_max_f32_e64 v14, -v9, 0
	s_mov_b32 s0, 0x800000
	v_add_f32_e32 v9, 1.0, v13
	v_add_f32_e32 v11, 1.0, v11
	v_cmp_gt_f32_e32 vcc, s0, v9
	v_rcp_f32_e32 v129, v11
	s_mov_b32 s0, 0x3f317217
	v_cndmask_b32_e64 v11, 0, 32, vcc
	v_ldexp_f32 v9, v9, v11
	v_log_f32_e32 v11, v9
	v_add_f32_e32 v9, -1.0, v129
	v_fma_f32 v9, v12, v9, 1.0
	v_pk_mul_f32 v[34:35], v[2:3], v[8:9] op_sel_hi:[0,1]
	v_mul_f32_e32 v8, 0x3f317217, v11
	v_fma_f32 v8, v11, s0, -v8
	v_fmac_f32_e32 v8, 0x3377d1cf, v11
	s_mov_b32 s0, 0x7f800000
	v_cndmask_b32_e32 v13, 0, v178, vcc
	v_fmac_f32_e32 v8, 0x3f317217, v11
	v_cmp_lt_f32_e64 vcc, |v11|, s0
	v_mov_b32_e32 v9, v34
	s_nop 0
	v_cndmask_b32_e32 v8, v11, v8, vcc
	v_sub_f32_e32 v8, v8, v13
	v_add_f32_e32 v8, v14, v8
	v_sub_f32_e32 v8, -0.5, v8
	v_mul_f32_e32 v8, 0x3fb8aa3b, v8
	v_exp_f32_e32 v12, v8
	v_mul_f32_e32 v8, v18, v35
	v_mov_b32_e32 v11, v34
	v_pk_fma_f32 v[68:69], v[10:11], v[8:9], v[68:69]
	v_xor_b32_e32 v132, 0x80000000, v12
.LBB0_1227:
	s_or_b64 exec, exec, s[6:7]
	s_and_saveexec_b64 s[6:7], s[4:5]
	s_xor_b64 s[6:7], exec, s[6:7]
	v_mov_b32_e32 v19, s91
	s_or_saveexec_b64 s[6:7], s[6:7]
	v_mov_b32_e32 v36, 0
	v_mov_b32_e32 v130, 0
	v_mov_b32_e32 v39, 0
	v_mov_b32_e32 v133, 0
	s_xor_b64 exec, exec, s[6:7]
	s_cbranch_execz .LBB0_1231
	v_mov_b32_e32 v9, v203
	v_mov_b32_e32 v11, v211
	v_mov_b32_e32 v12, v219
	v_mov_b32_e32 v37, v227
	v_mov_b32_e32 v8, v235
	s_mov_b32 s0, 0xbfb8aa3b
	v_mov_b32_e32 v10, v19
	v_add_f32_e32 v9, v108, v9
	v_mul_f32_e64 v13, |v9|, s0
	v_add_f32_e32 v11, v116, v11
	v_exp_f32_e32 v13, v13
	v_mul_f32_e32 v11, 0xbfb8aa3b, v11
	v_exp_f32_e32 v14, v11
	s_mov_b32 s0, 0x800000
	v_add_f32_e32 v13, 1.0, v13
	v_cmp_gt_f32_e32 vcc, s0, v13
	v_add_f32_e32 v14, 1.0, v14
	v_rcp_f32_e32 v130, v14
	v_cndmask_b32_e64 v15, 0, 32, vcc
	v_ldexp_f32 v13, v13, v15
	v_log_f32_e32 v13, v13
	v_add_f32_e32 v15, -1.0, v130
	v_fma_f32 v12, v12, v15, 1.0
	s_mov_b32 s0, 0x3f317217
	v_mul_f32_e32 v15, 0x3f317217, v13
	v_fma_f32 v15, v13, s0, -v15
	v_fmac_f32_e32 v15, 0x3377d1cf, v13
	s_mov_b32 s0, 0x7f800000
	v_cndmask_b32_e32 v14, 0, v178, vcc
	v_fmac_f32_e32 v15, 0x3f317217, v13
	v_cmp_lt_f32_e64 vcc, |v13|, s0
	v_max_f32_e64 v9, -v9, 0
	v_mov_b32_e32 v11, v3
	v_cndmask_b32_e32 v13, v13, v15, vcc
	v_sub_f32_e32 v13, v13, v14
	v_add_f32_e32 v9, v9, v13
	v_sub_f32_e32 v9, -0.5, v9
	v_mul_f32_e32 v9, 0x3fb8aa3b, v9
	v_exp_f32_e32 v13, v9
	v_mul_f32_e32 v36, v3, v12
	v_pk_mul_f32 v[38:39], v[10:11], v[36:37]
	v_xor_b32_e32 v133, 0x80000000, v13
	v_mov_b32_e32 v9, v39
	v_pk_fma_f32 v[68:69], v[8:9], v[38:39], v[68:69]
.LBB0_1231:
	s_or_b64 exec, exec, s[6:7]
	s_and_saveexec_b64 s[6:7], s[4:5]
	s_xor_b64 s[6:7], exec, s[6:7]
	v_mov_b32_e32 v20, s91
	s_or_saveexec_b64 s[6:7], s[6:7]
	v_mov_b32_e32 v40, 0
	v_mov_b32_e32 v37, 0
	v_mov_b32_e32 v67, 0
	v_mov_b32_e32 v134, 0
	s_xor_b64 exec, exec, s[6:7]
	s_cbranch_execz .LBB0_1235
	v_mov_b32_e32 v9, v204
	v_mov_b32_e32 v11, v212
	v_mov_b32_e32 v12, v220
	v_mov_b32_e32 v41, v228
	v_mov_b32_e32 v8, v236
	s_mov_b32 s0, 0xbfb8aa3b
	v_mov_b32_e32 v10, v20
	v_add_f32_e32 v9, v109, v9
	v_mul_f32_e64 v13, |v9|, s0
	v_add_f32_e32 v11, v117, v11
	v_exp_f32_e32 v13, v13
	v_mul_f32_e32 v11, 0xbfb8aa3b, v11
	v_exp_f32_e32 v14, v11
	s_mov_b32 s0, 0x800000
	v_add_f32_e32 v13, 1.0, v13
	v_cmp_gt_f32_e32 vcc, s0, v13
	v_add_f32_e32 v14, 1.0, v14
	v_rcp_f32_e32 v37, v14
	v_cndmask_b32_e64 v15, 0, 32, vcc
	v_ldexp_f32 v13, v13, v15
	v_log_f32_e32 v13, v13
	v_add_f32_e32 v15, -1.0, v37
	v_fma_f32 v12, v12, v15, 1.0
	s_mov_b32 s0, 0x3f317217
	v_mul_f32_e32 v15, 0x3f317217, v13
	v_fma_f32 v15, v13, s0, -v15
	v_fmac_f32_e32 v15, 0x3377d1cf, v13
	s_mov_b32 s0, 0x7f800000
	v_cndmask_b32_e32 v14, 0, v178, vcc
	v_fmac_f32_e32 v15, 0x3f317217, v13
	v_cmp_lt_f32_e64 vcc, |v13|, s0
	v_max_f32_e64 v9, -v9, 0
	v_mov_b32_e32 v11, v4
	v_cndmask_b32_e32 v13, v13, v15, vcc
	v_sub_f32_e32 v13, v13, v14
	v_add_f32_e32 v9, v9, v13
	v_sub_f32_e32 v9, -0.5, v9
	v_mul_f32_e32 v9, 0x3fb8aa3b, v9
	v_exp_f32_e32 v13, v9
	v_mul_f32_e32 v40, v4, v12
	v_pk_mul_f32 v[66:67], v[10:11], v[40:41]
	v_xor_b32_e32 v134, 0x80000000, v13
	v_mov_b32_e32 v9, v67
	v_pk_fma_f32 v[68:69], v[8:9], v[66:67], v[68:69]
; __device__ __forceinline__ float sigmoidf_(float x) { return __builtin_amdgcn_rcpf(1.0f + __expf(-x)); }
; __device__ __forceinline__ float softplusf_(float x) { return fmaxf(x, 0.f) + __logf(1.0f + __expf(-fabsf(x))); }
; __device__ __forceinline__ void phase_rwkv_ra(const Ctx& c, int p, int l) {
;     ...
;             float ssq = 0.f, bsum = 0.f;
; #pragma unroll
;             for (int e = 0; e < 8; ++e) {
;                 if (valid) {
;                     const float wlog = -softplusf_(-(pw0[e] + wpf[e])) - 0.5f; lw[e] = -__expf(wlog);
;                     const float a = sigmoidf_(pa0[e] + apf[e]); const float kk = kf[e] * pkk[e]; ssq += kk * kk;
;                     kp[e] = kf[e] * (1.0f + (a - 1.0f) * pka[e]); bsum += rf[e] * kp[e] * prk[e]; av[e] = kk; bv[e] = a;
;                 } else { lw[e] = 0.f; rf[e] = 0.f; kp[e] = 0.f; av[e] = 0.f; bv[e] = 0.f; }
;             }
.LBB0_1235:
	s_or_b64 exec, exec, s[6:7]
	s_and_saveexec_b64 s[6:7], s[4:5]
	s_xor_b64 s[6:7], exec, s[6:7]
	v_mov_b32_e32 v21, s91
	s_or_saveexec_b64 s[6:7], s[6:7]
	v_mov_b32_e32 v74, 0
	v_mov_b32_e32 v38, 0
	v_mov_b32_e32 v79, 0
	v_mov_b32_e32 v135, 0
	s_xor_b64 exec, exec, s[6:7]
	s_cbranch_execz .LBB0_1239
	v_mov_b32_e32 v9, v205
	v_mov_b32_e32 v11, v213
	v_mov_b32_e32 v12, v221
	v_mov_b32_e32 v75, v229
	v_mov_b32_e32 v8, v237
	s_mov_b32 s0, 0xbfb8aa3b
	v_mov_b32_e32 v10, v21
	v_add_f32_e32 v9, v110, v9
	v_mul_f32_e64 v13, |v9|, s0
	v_add_f32_e32 v11, v118, v11
	v_exp_f32_e32 v13, v13
	v_mul_f32_e32 v11, 0xbfb8aa3b, v11
	v_exp_f32_e32 v14, v11
	s_mov_b32 s0, 0x800000
	v_add_f32_e32 v13, 1.0, v13
	v_cmp_gt_f32_e32 vcc, s0, v13
	v_add_f32_e32 v14, 1.0, v14
	v_rcp_f32_e32 v38, v14
	v_cndmask_b32_e64 v15, 0, 32, vcc
	v_ldexp_f32 v13, v13, v15
	v_log_f32_e32 v13, v13
	v_add_f32_e32 v15, -1.0, v38
	v_fma_f32 v12, v12, v15, 1.0
	s_mov_b32 s0, 0x3f317217
	v_mul_f32_e32 v15, 0x3f317217, v13
	v_fma_f32 v15, v13, s0, -v15
	v_fmac_f32_e32 v15, 0x3377d1cf, v13
	s_mov_b32 s0, 0x7f800000
	v_cndmask_b32_e32 v14, 0, v178, vcc
	v_fmac_f32_e32 v15, 0x3f317217, v13
	v_cmp_lt_f32_e64 vcc, |v13|, s0
	v_max_f32_e64 v9, -v9, 0
	v_mov_b32_e32 v11, v5
	v_cndmask_b32_e32 v13, v13, v15, vcc
	v_sub_f32_e32 v13, v13, v14
	v_add_f32_e32 v9, v9, v13
	v_sub_f32_e32 v9, -0.5, v9
	v_mul_f32_e32 v9, 0x3fb8aa3b, v9
	v_exp_f32_e32 v13, v9
	v_mul_f32_e32 v74, v5, v12
	v_pk_mul_f32 v[78:79], v[10:11], v[74:75]
	v_xor_b32_e32 v135, 0x80000000, v13
	v_mov_b32_e32 v9, v79
	v_pk_fma_f32 v[68:69], v[8:9], v[78:79], v[68:69]
.LBB0_1239:
	s_or_b64 exec, exec, s[6:7]
	s_and_saveexec_b64 s[6:7], s[4:5]
	s_xor_b64 s[6:7], exec, s[6:7]
	v_mov_b32_e32 v22, s91
	s_or_saveexec_b64 s[6:7], s[6:7]
	v_mov_b32_e32 v80, 0
	v_mov_b32_e32 v66, 0
	v_mov_b32_e32 v83, 0
	v_mov_b32_e32 v144, 0
	s_xor_b64 exec, exec, s[6:7]
	s_cbranch_execz .LBB0_1243
	v_mov_b32_e32 v9, v206
	v_mov_b32_e32 v11, v214
	v_mov_b32_e32 v12, v222
	v_mov_b32_e32 v81, v230
	v_mov_b32_e32 v8, v238
	s_mov_b32 s0, 0xbfb8aa3b
	v_mov_b32_e32 v10, v22
	v_add_f32_e32 v9, v111, v9
	v_mul_f32_e64 v13, |v9|, s0
	v_add_f32_e32 v11, v119, v11
	v_exp_f32_e32 v13, v13
	v_mul_f32_e32 v11, 0xbfb8aa3b, v11
	v_exp_f32_e32 v14, v11
	s_mov_b32 s0, 0x800000
	v_add_f32_e32 v13, 1.0, v13
	v_cmp_gt_f32_e32 vcc, s0, v13
	v_add_f32_e32 v14, 1.0, v14
	v_rcp_f32_e32 v66, v14
	v_cndmask_b32_e64 v15, 0, 32, vcc
	v_ldexp_f32 v13, v13, v15
	v_log_f32_e32 v13, v13
	v_add_f32_e32 v15, -1.0, v66
	v_fma_f32 v12, v12, v15, 1.0
	s_mov_b32 s0, 0x3f317217
	v_mul_f32_e32 v15, 0x3f317217, v13
	v_fma_f32 v15, v13, s0, -v15
	v_fmac_f32_e32 v15, 0x3377d1cf, v13
	s_mov_b32 s0, 0x7f800000
	v_cndmask_b32_e32 v14, 0, v178, vcc
	v_fmac_f32_e32 v15, 0x3f317217, v13
	v_cmp_lt_f32_e64 vcc, |v13|, s0
	v_max_f32_e64 v9, -v9, 0
	v_mov_b32_e32 v11, v6
	v_cndmask_b32_e32 v13, v13, v15, vcc
	v_sub_f32_e32 v13, v13, v14
	v_add_f32_e32 v9, v9, v13
	v_sub_f32_e32 v9, -0.5, v9
	v_mul_f32_e32 v9, 0x3fb8aa3b, v9
	v_exp_f32_e32 v13, v9
	v_mul_f32_e32 v80, v6, v12
	v_pk_mul_f32 v[82:83], v[10:11], v[80:81]
	v_xor_b32_e32 v144, 0x80000000, v13
	v_mov_b32_e32 v9, v83
	v_pk_fma_f32 v[68:69], v[8:9], v[82:83], v[68:69]
.LBB0_1243:
	s_or_b64 exec, exec, s[6:7]
	s_and_saveexec_b64 s[6:7], s[4:5]
	s_xor_b64 s[4:5], exec, s[6:7]
	v_mov_b32_e32 v23, s91
	v_mov_b64_e32 v[8:9], v[16:17]
	v_mov_b64_e32 v[10:11], v[18:19]
	v_mov_b64_e32 v[12:13], v[20:21]
	v_mov_b64_e32 v[14:15], v[22:23]
	s_or_saveexec_b64 s[4:5], s[4:5]
	v_mov_b32_e32 v81, 0
	v_mov_b32_e32 v82, 0
	v_mov_b32_e32 v84, 0
	v_mov_b32_e32 v85, 0
	s_xor_b64 exec, exec, s[4:5]
	s_cbranch_execz .LBB0_1247
	v_mov_b32_e32 v9, v207
	v_mov_b32_e32 v11, v215
	v_mov_b32_e32 v13, v223
	v_mov_b32_e32 v8, v231
	v_mov_b32_e32 v10, v239
	s_mov_b32 s0, 0xbfb8aa3b
	v_add_f32_e32 v9, v112, v9
	v_mul_f32_e64 v12, |v9|, s0
	v_add_f32_e32 v11, v120, v11
	v_exp_f32_e32 v14, v12
	v_mul_f32_e32 v11, 0xbfb8aa3b, v11
	v_exp_f32_e32 v11, v11
	v_max_f32_e64 v15, -v9, 0
	v_add_f32_e32 v9, 1.0, v14
	s_mov_b32 s0, 0x800000
	v_cmp_gt_f32_e32 vcc, s0, v9
	v_add_f32_e32 v11, 1.0, v11
	v_rcp_f32_e32 v81, v11
	v_cndmask_b32_e64 v14, 0, 32, vcc
	v_ldexp_f32 v9, v9, v14
	v_log_f32_e32 v11, v9
	v_add_f32_e32 v9, -1.0, v81
	v_mov_b32_e32 v12, v7
	v_fma_f32 v9, v13, v9, 1.0
	v_mul_f32_e32 v13, 0x3f317217, v11
	s_mov_b32 s0, 0x3f317217
	v_pk_mul_f32 v[84:85], v[12:13], v[8:9] op_sel_hi:[0,1]
	v_fma_f32 v9, v11, s0, -v13
	v_fmac_f32_e32 v9, 0x3377d1cf, v11
	s_mov_b32 s0, 0x7f800000
	v_cndmask_b32_e32 v14, 0, v178, vcc
	v_fmac_f32_e32 v9, 0x3f317217, v11
	v_cmp_lt_f32_e64 vcc, |v11|, s0
	v_mul_f32_e32 v8, v23, v85
	s_nop 0
	v_cndmask_b32_e32 v9, v11, v9, vcc
	v_sub_f32_e32 v9, v9, v14
	v_add_f32_e32 v9, v15, v9
	v_sub_f32_e32 v9, -0.5, v9
	v_mul_f32_e32 v9, 0x3fb8aa3b, v9
	v_exp_f32_e32 v12, v9
	v_mov_b32_e32 v11, v84
	v_mov_b32_e32 v9, v84
	v_pk_fma_f32 v[68:69], v[10:11], v[8:9], v[68:69]
	v_xor_b32_e32 v82, 0x80000000, v12
	v_mov_b64_e32 v[8:9], v[16:17]
	v_mov_b64_e32 v[10:11], v[18:19]
	v_mov_b64_e32 v[12:13], v[20:21]
	v_mov_b64_e32 v[14:15], v[22:23]

; __device__ __forceinline__ void mlstm_task(const Ctx& c, int p, int l, int q, int h, int slab) {
;     ...
;         __syncthreads();
;         f32x4 num = {0.f, 0.f, 0.f, 0.f};
;         num = mma_tile(St + 16 * ti * 72, 72, VT + 16 * vj * 72, 72, 64, num, lane);
; #pragma unroll
;         for (int r = 0; r < 4; ++r) { const int t = 16 * ti + (lane >> 4) * 4 + r; num[r] = qc[r] * wint[t] + esc[t] * num[r]; }
;         if (w < 4) {
;             f32x4 sv2 = {0.f, 0.f, 0.f, 0.f};
;             sv2 = mma_tile(St + 16 * w * 72, 72, VT + 32 * 72, 72, 64, sv2, lane);
; #pragma unroll
;             for (int r = 0; r < 4; ++r) { const int t = 16 * w + (lane >> 4) * 4 + r; qc2[r] = qc2[r] * wint[t] + esc[t] * sv2[r]; }
;             if ((lane & 15) == 0) {
; #pragma unroll
;                 for (int r = 0; r < 4; ++r) { const int t = 16 * w + (lane >> 4) * 4 + r; dd[t] = fmaxf(fabsf(qc2[r]), __expf(-mts[t])); }
;             }
.LBB0_1631:
	s_nop 2
	ds_read_b128 v[4:7], v122
	ds_read_b128 v[84:87], v123
	s_and_b64 vcc, exec, s[68:69]
	s_waitcnt lgkmcnt(0)
	v_mfma_f32_16x16x32_bf16 v[4:7], v[4:7], v[84:87], 0
	ds_read_b128 v[84:87], v122 offset:64
	ds_read_b128 v[106:109], v123 offset:64
	s_waitcnt lgkmcnt(0)
	v_mfma_f32_16x16x32_bf16 v[4:7], v[84:87], v[106:109], v[4:7]
	ds_read2_b32 v[110:111], v147 offset1:1
	ds_read2_b32 v[112:113], v148 offset1:1
	ds_read2_b32 v[106:107], v149 offset1:1
	ds_read2_b32 v[108:109], v150 offset1:1
	s_cbranch_vccnz .LBB0_1635
	ds_read_b128 v[84:87], v197
	ds_read_b128 v[200:203], v131
	s_waitcnt lgkmcnt(0)
	v_mfma_f32_16x16x32_bf16 v[84:87], v[84:87], v[200:203], 0
	ds_read_b128 v[200:203], v197 offset:64
	ds_read_b128 v[204:207], v131 offset:64
	s_waitcnt lgkmcnt(0)
	v_mfma_f32_16x16x32_bf16 v[84:87], v[200:203], v[204:207], v[84:87]
	s_and_saveexec_b64 s[68:69], s[30:31]
	s_cbranch_execz .LBB0_1634
	ds_read2_b32 v[136:137], v153 offset1:1
	ds_read2_b32 v[138:139], v154 offset1:1
	ds_read2_b32 v[200:201], v151 offset1:1
	ds_read2_b32 v[202:203], v152 offset1:1
	s_waitcnt lgkmcnt(2)
	s_nop 0
	v_mul_f32_e32 v13, v87, v139
	v_fmac_f32_e32 v13, v11, v137
	s_waitcnt lgkmcnt(0)
	v_mul_f32_e32 v11, v84, v202
	v_mul_f32_e32 v84, v85, v203
	v_fmac_f32_e32 v11, v8, v200
	v_fmac_f32_e32 v84, v9, v201
	ds_read2_b32 v[8:9], v155 offset1:1
	v_mul_f32_e32 v85, v86, v138
	v_fmac_f32_e32 v85, v10, v136
	s_waitcnt lgkmcnt(0)
	v_mul_f32_e32 v8, 0xbfb8aa3b, v8
	v_mul_f32_e32 v9, 0xbfb8aa3b, v9
	v_exp_f32_e32 v8, v8
	v_exp_f32_e32 v9, v9
	v_max_f32_e64 v8, |v11|, v8
	v_max_f32_e64 v9, |v84|, v9
	ds_write2_b32 v156, v8, v9 offset1:1
	ds_read2_b32 v[8:9], v157 offset1:1
	s_waitcnt lgkmcnt(0)
	v_mul_f32_e32 v8, 0xbfb8aa3b, v8
	v_mul_f32_e32 v9, 0xbfb8aa3b, v9
	v_exp_f32_e32 v8, v8
	v_exp_f32_e32 v9, v9
	v_max_f32_e64 v8, |v85|, v8
	v_max_f32_e64 v9, |v13|, v9
	ds_write2_b32 v158, v8, v9 offset1:1
